# v10 plus hgrn local: second chunk rows prefetched with the first, lower bound reused
# speedup vs baseline: 1.0062x; 1.0062x over previous
; #define LAS __attribute__((address_space(3)))
; #define LDS_WAIT() asm volatile("s_waitcnt lgkmcnt(0)" ::: "memory")
; __device__ __forceinline__ float bf1(bf16 h) { return __uint_as_float(((unsigned)h) << 16); }
; template <bool OUT> __device__ __forceinline__ HRaw hgrn_loadc(const PA& a, int bh, int c, int chunk, int lane) {
;     const bf16* pr = (const bf16*)(a.ws + WS_PROJ) + ((size_t)(bh >> 2) * T + (size_t)c * 128 + chunk * 16 + (lane >> 3)) * DIN + (bh & 3) * 64 + (lane & 7) * 8;
;     HRaw r;
; #pragma unroll
;     for (int k = 0; k < 2; ++k) { r.f[k] = *(const v4u*)(pr + (size_t)(8 * k) * DIN + 256); r.v[k] = *(const v4u*)(pr + (size_t)(8 * k) * DIN + 512);
;         if (OUT) { r.q[k] = *(const v4u*)(pr + (size_t)(8 * k) * DIN); } }
; template <bool OUT> __device__ __forceinline__ void hgrn_chunk(const PA& a, LAS unsigned char* wb, LAS float* DLk, LAS float* E7k, LAS float* DALLk, int layer, int h, int lane, const HRaw& raw, ...
;     ...
;     LDS_WAIT();
;     {
;         const int rr = lane >> 3, cc = (lane & 7) * 8;
; #pragma unroll
;         for (int k = 0; k < 2; ++k) { *(LAS v4u*)(RF + (rr + 8 * k) * 72 + cc) = raw.f[k]; *(LAS v4u*)(RV + (rr + 8 * k) * 72 + cc) = raw.v[k]; if (OUT) *(LAS v4u*)(RQ + (rr + 8 * k) * 72 + cc) = raw.q[k]; }
;         LDS_WAIT();
;         const float lb = (layer == 0) ? 0.f : sigmf(a.in[4][256 + h * 64 + lane] - a.in[4][h * 64 + lane]);
;         {
;             u16 vr[16];
; #pragma unroll
;             for (int t = 0; t < 16; ++t) vr[t] = RV[t * 72 + lane];
;             const v4u w0 = {(unsigned)vr[0] | ((unsigned)vr[1] << 16), (unsigned)vr[2] | ((unsigned)vr[3] << 16), (unsigned)vr[4] | ((unsigned)vr[5] << 16), (unsigned)vr[6] | ((unsigned)vr[7] << 16)};
;             const v4u w1 = {(unsigned)vr[8] | ((unsigned)vr[9] << 16), (unsigned)vr[10] | ((unsigned)vr[11] << 16), (unsigned)vr[12] | ((unsigned)vr[13] << 16), (unsigned)vr[14] | ((unsigned)vr[15] << 16)};
;             *(LAS v4u*)(VT + lane * 24) = w0; *(LAS v4u*)(VT + lane * 24 + 8) = w1;
;         }
;         float cum[16], kk[16]; float run = 0.f;
; #pragma unroll
;         for (int t = 0; t < 16; ++t) { const float sg = sigmf(bf1(RF[t * 72 + lane])); const float f = lb + (1.f - lb) * sg; kk[t] = (1.f - lb) * (1.f - sg); run += fmaxf(__logf(f), -69.f); cum[t] = run; }
.LBB0_460:
	s_and_b32 s3, s30, 31
	s_ashr_i32 s2, s30, 5
	s_xor_b32 s24, s3, 63
	s_and_b64 s[0:1], s[10:11], exec
	s_cselect_b32 s31, s3, s24
	s_ashr_i32 s0, s30, 7
	s_ashr_i32 s1, s0, 31
	s_lshl_b64 s[24:25], s[0:1], 13
	s_lshl_b32 s0, s31, 7
	s_or_b32 s24, s24, s0
	v_or_b32_e32 v2, s24, v142
	v_mov_b64_e32 v[0:1], s[60:61]
	s_lshl_b32 s37, s2, 6
	v_mad_u64_u32 v[0:1], s[0:1], v2, s93, v[0:1]
	v_mov_b32_e32 v2, 0x1c00
	s_and_b32 s0, s37, 0xc0
	v_mad_i32_i24 v1, s25, v2, v1
	s_lshl_b32 s62, s0, 1
	v_lshl_add_u64 v[0:1], v[0:1], 0, s[62:63]
	v_lshl_add_u64 v[8:9], v[0:1], 0, v[220:221]
	v_add_co_u32_e32 v12, vcc, s55, v8
	s_nop 1
	v_addc_co_u32_e32 v13, vcc, 0, v9, vcc
	s_barrier
	global_load_dwordx4 v[0:3], v[8:9], off offset:512
	global_load_dwordx4 v[4:7], v[8:9], off offset:1024
	s_nop 0
	global_load_dwordx4 v[8:11], v[12:13], off offset:512
	s_nop 0
	global_load_dwordx4 v[12:15], v[12:13], off offset:1024
	v_ashrrev_i32_e32 v180, 3, v140
	v_mov_b32_e32 v181, s24
	v_or_b32_e32 v181, s12, v181
	v_add_u32_e32 v180, v181, v180
	v_mul_lo_u32 v180, v180, s93
	v_and_b32_e32 v181, 7, v140
	v_lshlrev_b32_e32 v181, 4, v181
	v_add3_u32 v180, v180, v181, s62
	global_load_dwordx4 v[160:163], v180, s[60:61] offset:512
	global_load_dwordx4 v[164:167], v180, s[60:61] offset:1024
	v_add_u32_e32 v181, s55, v180
	global_load_dwordx4 v[168:171], v181, s[60:61] offset:512
	global_load_dwordx4 v[172:175], v181, s[60:61] offset:1024
	s_waitcnt lgkmcnt(0)
	s_and_b32 s38, s2, 3
	s_andn2_b64 vcc, exec, s[4:5]
	s_waitcnt vmcnt(7)
	ds_write_b128 v143, v[0:3]
	s_waitcnt vmcnt(6)
	ds_write_b128 v143, v[4:7] offset:2304
	s_waitcnt vmcnt(5)
	ds_write_b128 v143, v[8:11] offset:1152
	s_waitcnt vmcnt(4)
	ds_write_b128 v143, v[12:15] offset:3456
	s_waitcnt lgkmcnt(0)
	v_cndmask_b32_e64 v1, 0, 1, s[4:5]
	v_mov_b32_e32 v0, 0
	v_cmp_ne_u32_e64 s[0:1], 1, v1
	v_mov_b32_e32 v1, 0
	s_cbranch_vccnz .LBB0_462
	v_readlane_b32 s2, v253, 12
	v_readlane_b32 s3, v253, 13
	v_lshlrev_b32_e32 v1, 2, v140
	v_mov_b32_e32 v5, v221
	v_lshl_or_b32 v4, s38, 8, v1
	s_nop 1
	global_load_dwordx2 v[2:3], v221, s[2:3]
	s_waitcnt vmcnt(0)
	v_lshl_add_u64 v[2:3], v[2:3], 0, v[4:5]
	flat_load_dword v1, v[2:3] offset:1024
	s_nop 0
	flat_load_dword v2, v[2:3]
	s_waitcnt vmcnt(0) lgkmcnt(0)
	v_sub_f32_e32 v1, v1, v2
	v_mul_f32_e32 v1, 0xbfb8aa3b, v1
	v_exp_f32_e32 v1, v1
	s_nop 0
	v_add_f32_e32 v1, 1.0, v1
	v_rcp_f32_e32 v1, v1
.LBB0_462:
	s_nop 0
	v_mov_b32_e32 v177, v1
	ds_read_u16 v2, v146 offset:2304
	ds_read_u16 v6, v146 offset:2448
	ds_read_u16 v3, v146 offset:2592
	ds_read_u16 v7, v146 offset:2736
	ds_read_u16 v4, v146 offset:2880
	ds_read_u16 v8, v146 offset:3024
	ds_read_u16 v5, v146 offset:3168
	ds_read_u16 v9, v146 offset:3312
	ds_read_u16 v10, v146 offset:3456
	ds_read_u16 v11, v146 offset:3600
	ds_read_u16 v12, v146 offset:3744
	ds_read_u16 v13, v146 offset:3888
	ds_read_u16 v14, v146 offset:4032
	ds_read_u16 v15, v146 offset:4176
	ds_read_u16 v16, v146 offset:4320
	ds_read_u16 v17, v146 offset:4464
	s_mov_b32 s2, 0x5040100
	s_waitcnt lgkmcnt(8)
	v_perm_b32 v5, v9, v5, s2
	v_perm_b32 v4, v8, v4, s2
	v_perm_b32 v3, v7, v3, s2
	v_perm_b32 v2, v6, v2, s2
	s_waitcnt lgkmcnt(0)
	v_perm_b32 v9, v17, v16, s2
	v_perm_b32 v8, v15, v14, s2
	v_perm_b32 v7, v13, v12, s2
	v_perm_b32 v6, v11, v10, s2
	ds_write_b128 v147, v[2:5] offset:7680
	ds_write_b128 v147, v[6:9] offset:7696
	ds_read_u16 v3, v148
	v_sub_f32_e32 v2, 1.0, v1
	s_waitcnt lgkmcnt(0)
	v_lshlrev_b32_e32 v3, 16, v3
	v_mul_f32_e32 v3, 0xbfb8aa3b, v3
	v_exp_f32_e32 v3, v3
	s_nop 0
	v_add_f32_e32 v3, 1.0, v3
	v_rcp_f32_e32 v4, v3
	s_nop 0
	v_fma_f32 v3, v2, v4, v1
	v_cmp_gt_f32_e32 vcc, s27, v3
	s_nop 1
	v_cndmask_b32_e64 v5, 0, 32, vcc
	v_ldexp_f32 v3, v3, v5
	v_log_f32_e32 v3, v3
	s_nop 0
	v_mul_f32_e32 v5, 0x3f317217, v3
	v_fma_f32 v5, v3, s80, -v5
	v_fmac_f32_e32 v5, 0x3377d1cf, v3
	v_fmac_f32_e32 v5, 0x3f317217, v3
	v_cmp_lt_f32_e64 s[42:43], |v3|, s81
	s_nop 1
	v_cndmask_b32_e64 v3, v3, v5, s[42:43]
	v_cndmask_b32_e32 v5, 0, v238, vcc
	v_sub_f32_e32 v3, v3, v5
	ds_read_u16 v5, v148 offset:144
	v_max_f32_e32 v3, 0xc28a0000, v3
	v_add_f32_e32 v3, 0, v3
	s_waitcnt lgkmcnt(0)
	v_lshlrev_b32_e32 v5, 16, v5
	v_mul_f32_e32 v5, 0xbfb8aa3b, v5
	v_exp_f32_e32 v5, v5
	s_nop 0
	v_add_f32_e32 v5, 1.0, v5
	v_rcp_f32_e32 v6, v5
	s_nop 0
	v_fma_f32 v5, v2, v6, v1
	v_cmp_gt_f32_e32 vcc, s27, v5
	s_nop 1
	v_cndmask_b32_e64 v7, 0, 32, vcc
	v_ldexp_f32 v5, v5, v7
	v_log_f32_e32 v5, v5
	s_nop 0
	v_mul_f32_e32 v7, 0x3f317217, v5
	v_fma_f32 v7, v5, s80, -v7
	v_fmac_f32_e32 v7, 0x3377d1cf, v5
	v_fmac_f32_e32 v7, 0x3f317217, v5
	v_cmp_lt_f32_e64 s[42:43], |v5|, s81
	s_nop 1
	v_cndmask_b32_e64 v5, v5, v7, s[42:43]
	v_cndmask_b32_e32 v7, 0, v238, vcc
	v_sub_f32_e32 v5, v5, v7
	v_max_f32_e32 v5, 0xc28a0000, v5
	v_add_f32_e32 v20, v3, v5
	ds_read_u16 v5, v148 offset:288
	s_waitcnt lgkmcnt(0)
	v_lshlrev_b32_e32 v5, 16, v5
	v_mul_f32_e32 v5, 0xbfb8aa3b, v5
	v_exp_f32_e32 v5, v5
	s_nop 0
	v_add_f32_e32 v5, 1.0, v5
	v_rcp_f32_e32 v5, v5
	s_nop 0
	v_fma_f32 v7, v2, v5, v1
	v_cmp_gt_f32_e32 vcc, s27, v7
	v_pk_add_f32 v[4:5], v[4:5], 1.0 op_sel_hi:[1,0] neg_lo:[1,0] neg_hi:[1,0]
	s_nop 0
	v_cndmask_b32_e64 v8, 0, 32, vcc
	v_ldexp_f32 v7, v7, v8
	v_log_f32_e32 v7, v7
	s_nop 0
	v_mul_f32_e32 v8, 0x3f317217, v7
	v_fma_f32 v8, v7, s80, -v8
	v_fmac_f32_e32 v8, 0x3377d1cf, v7
	v_fmac_f32_e32 v8, 0x3f317217, v7
	v_cmp_lt_f32_e64 s[42:43], |v7|, s81
	s_nop 1
	v_cndmask_b32_e64 v7, v7, v8, s[42:43]
	v_cndmask_b32_e32 v8, 0, v238, vcc
	v_sub_f32_e32 v7, v7, v8
	v_max_f32_e32 v7, 0xc28a0000, v7
	v_add_f32_e32 v21, v20, v7
	ds_read_u16 v7, v148 offset:432
	s_waitcnt lgkmcnt(0)
; __device__ __forceinline__ float bf1(bf16 h) { return __uint_as_float(((unsigned)h) << 16); }
; __device__ __forceinline__ float sigmf(float v) { return __builtin_amdgcn_rcpf(1.0f + __builtin_amdgcn_exp2f(-1.4426950408889634f * v)); }
; template <bool OUT> __device__ __forceinline__ void hgrn_chunk(const PA& a, LAS unsigned char* wb, LAS float* DLk, LAS float* E7k, LAS float* DALLk, int layer, int h, int lane, const HRaw& raw, ...
;     ...
;         float cum[16], kk[16]; float run = 0.f;
; #pragma unroll
;         for (int t = 0; t < 16; ++t) { const float sg = sigmf(bf1(RF[t * 72 + lane])); const float f = lb + (1.f - lb) * sg; kk[t] = (1.f - lb) * (1.f - sg); run += fmaxf(__logf(f), -69.f); cum[t] = run; }
	v_lshlrev_b32_e32 v7, 16, v7
	v_mul_f32_e32 v7, 0xbfb8aa3b, v7
	v_exp_f32_e32 v7, v7
	s_nop 0
	v_add_f32_e32 v7, 1.0, v7
	v_rcp_f32_e32 v7, v7
	s_nop 0
	v_fma_f32 v8, v2, v7, v1
	v_cmp_gt_f32_e32 vcc, s27, v8
	v_pk_add_f32 v[6:7], v[6:7], 1.0 op_sel_hi:[1,0] neg_lo:[1,0] neg_hi:[1,0]
	s_nop 0
	v_cndmask_b32_e64 v9, 0, 32, vcc
	v_ldexp_f32 v8, v8, v9
	v_log_f32_e32 v8, v8
	s_nop 0
	v_mul_f32_e32 v9, 0x3f317217, v8
	v_fma_f32 v9, v8, s80, -v9
	v_fmac_f32_e32 v9, 0x3377d1cf, v8
	v_fmac_f32_e32 v9, 0x3f317217, v8
	v_cmp_lt_f32_e64 s[42:43], |v8|, s81
	s_nop 1
	v_cndmask_b32_e64 v8, v8, v9, s[42:43]
	v_cndmask_b32_e32 v9, 0, v238, vcc
	v_sub_f32_e32 v8, v8, v9
	v_max_f32_e32 v8, 0xc28a0000, v8
	v_add_f32_e32 v22, v21, v8
	ds_read_u16 v8, v148 offset:576
	s_waitcnt lgkmcnt(0)
	v_lshlrev_b32_e32 v8, 16, v8
	v_mul_f32_e32 v8, 0xbfb8aa3b, v8
	v_exp_f32_e32 v8, v8
	s_nop 0
	v_add_f32_e32 v8, 1.0, v8
	v_rcp_f32_e32 v8, v8
	s_nop 0
	v_fma_f32 v9, v2, v8, v1
	v_cmp_gt_f32_e32 vcc, s27, v9
	s_nop 1
	v_cndmask_b32_e64 v10, 0, 32, vcc
	v_ldexp_f32 v9, v9, v10
	v_log_f32_e32 v9, v9
	s_nop 0
	v_mul_f32_e32 v10, 0x3f317217, v9
	v_fma_f32 v10, v9, s80, -v10
	v_fmac_f32_e32 v10, 0x3377d1cf, v9
	v_fmac_f32_e32 v10, 0x3f317217, v9
	v_cmp_lt_f32_e64 s[42:43], |v9|, s81
	s_nop 1
	v_cndmask_b32_e64 v9, v9, v10, s[42:43]
	v_cndmask_b32_e32 v10, 0, v238, vcc
	v_sub_f32_e32 v9, v9, v10
	v_max_f32_e32 v9, 0xc28a0000, v9
	v_add_f32_e32 v23, v22, v9
	ds_read_u16 v9, v148 offset:720
	s_waitcnt lgkmcnt(0)
	v_lshlrev_b32_e32 v9, 16, v9
	v_mul_f32_e32 v9, 0xbfb8aa3b, v9
	v_exp_f32_e32 v9, v9
	s_nop 0
	v_add_f32_e32 v9, 1.0, v9
	v_rcp_f32_e32 v10, v9
	s_nop 0
	v_fma_f32 v9, v2, v10, v1
	v_cmp_gt_f32_e32 vcc, s27, v9
	s_nop 1
	v_cndmask_b32_e64 v11, 0, 32, vcc
	v_ldexp_f32 v9, v9, v11
	v_log_f32_e32 v9, v9
	s_nop 0
	v_mul_f32_e32 v11, 0x3f317217, v9
	v_fma_f32 v11, v9, s80, -v11
	v_fmac_f32_e32 v11, 0x3377d1cf, v9
	v_fmac_f32_e32 v11, 0x3f317217, v9
	v_cmp_lt_f32_e64 s[42:43], |v9|, s81
	s_nop 1
	v_cndmask_b32_e64 v9, v9, v11, s[42:43]
	v_cndmask_b32_e32 v11, 0, v238, vcc
	v_sub_f32_e32 v9, v9, v11
	v_max_f32_e32 v9, 0xc28a0000, v9
	v_add_f32_e32 v24, v23, v9
	ds_read_u16 v9, v148 offset:864
	s_waitcnt lgkmcnt(0)
	v_lshlrev_b32_e32 v9, 16, v9
	v_mul_f32_e32 v9, 0xbfb8aa3b, v9
	v_exp_f32_e32 v9, v9
	s_nop 0
	v_add_f32_e32 v9, 1.0, v9
	v_rcp_f32_e32 v9, v9
	s_nop 0
	v_fma_f32 v11, v2, v9, v1
	v_cmp_gt_f32_e32 vcc, s27, v11
	v_pk_add_f32 v[8:9], v[8:9], 1.0 op_sel_hi:[1,0] neg_lo:[1,0] neg_hi:[1,0]
	s_nop 0
	v_cndmask_b32_e64 v12, 0, 32, vcc
	v_ldexp_f32 v11, v11, v12
	v_log_f32_e32 v11, v11
	s_nop 0
	v_mul_f32_e32 v12, 0x3f317217, v11
	v_fma_f32 v12, v11, s80, -v12
	v_fmac_f32_e32 v12, 0x3377d1cf, v11
	v_fmac_f32_e32 v12, 0x3f317217, v11
	v_cmp_lt_f32_e64 s[42:43], |v11|, s81
	s_nop 1
	v_cndmask_b32_e64 v11, v11, v12, s[42:43]
	v_cndmask_b32_e32 v12, 0, v238, vcc
	v_sub_f32_e32 v11, v11, v12
	v_max_f32_e32 v11, 0xc28a0000, v11
	v_add_f32_e32 v25, v24, v11
	ds_read_u16 v11, v148 offset:1008
	s_waitcnt lgkmcnt(0)
	v_lshlrev_b32_e32 v11, 16, v11
	v_mul_f32_e32 v11, 0xbfb8aa3b, v11
	v_exp_f32_e32 v11, v11
	s_nop 0
	v_add_f32_e32 v11, 1.0, v11
	v_rcp_f32_e32 v11, v11
	s_nop 0
	v_fma_f32 v12, v2, v11, v1
	v_cmp_gt_f32_e32 vcc, s27, v12
	v_pk_add_f32 v[10:11], v[10:11], 1.0 op_sel_hi:[1,0] neg_lo:[1,0] neg_hi:[1,0]
	s_nop 0
	v_cndmask_b32_e64 v13, 0, 32, vcc
	v_ldexp_f32 v12, v12, v13
	v_log_f32_e32 v12, v12
	s_nop 0
	v_mul_f32_e32 v13, 0x3f317217, v12
	v_fma_f32 v13, v12, s80, -v13
	v_fmac_f32_e32 v13, 0x3377d1cf, v12
	v_fmac_f32_e32 v13, 0x3f317217, v12
	v_cmp_lt_f32_e64 s[42:43], |v12|, s81
	s_nop 1
	v_cndmask_b32_e64 v12, v12, v13, s[42:43]
	v_cndmask_b32_e32 v13, 0, v238, vcc
	v_sub_f32_e32 v12, v12, v13
	v_max_f32_e32 v12, 0xc28a0000, v12
	v_add_f32_e32 v26, v25, v12
	ds_read_u16 v12, v148 offset:1152
	s_waitcnt lgkmcnt(0)
	v_lshlrev_b32_e32 v12, 16, v12
	v_mul_f32_e32 v12, 0xbfb8aa3b, v12
	v_exp_f32_e32 v12, v12
	s_nop 0
	v_add_f32_e32 v12, 1.0, v12
	v_rcp_f32_e32 v12, v12
	s_nop 0
	v_fma_f32 v13, v2, v12, v1
	v_cmp_gt_f32_e32 vcc, s27, v13
	s_nop 1
	v_cndmask_b32_e64 v14, 0, 32, vcc
	v_ldexp_f32 v13, v13, v14
	v_log_f32_e32 v13, v13
	s_nop 0
	v_mul_f32_e32 v14, 0x3f317217, v13
	v_fma_f32 v14, v13, s80, -v14
	v_fmac_f32_e32 v14, 0x3377d1cf, v13
	v_fmac_f32_e32 v14, 0x3f317217, v13
	v_cmp_lt_f32_e64 s[42:43], |v13|, s81
	s_nop 1
	v_cndmask_b32_e64 v13, v13, v14, s[42:43]
	v_cndmask_b32_e32 v14, 0, v238, vcc
	v_sub_f32_e32 v13, v13, v14
	v_max_f32_e32 v13, 0xc28a0000, v13
	v_add_f32_e32 v27, v26, v13
	ds_read_u16 v13, v148 offset:1296
	s_waitcnt lgkmcnt(0)
	v_lshlrev_b32_e32 v13, 16, v13
	v_mul_f32_e32 v13, 0xbfb8aa3b, v13
	v_exp_f32_e32 v13, v13
	s_nop 0
	v_add_f32_e32 v13, 1.0, v13
	v_rcp_f32_e32 v14, v13
	s_nop 0
	v_fma_f32 v13, v2, v14, v1
	v_cmp_gt_f32_e32 vcc, s27, v13
	s_nop 1
	v_cndmask_b32_e64 v15, 0, 32, vcc
	v_ldexp_f32 v13, v13, v15
	v_log_f32_e32 v13, v13
	s_nop 0
	v_mul_f32_e32 v15, 0x3f317217, v13
	v_fma_f32 v15, v13, s80, -v15
	v_fmac_f32_e32 v15, 0x3377d1cf, v13
	v_fmac_f32_e32 v15, 0x3f317217, v13
	v_cmp_lt_f32_e64 s[42:43], |v13|, s81
	s_nop 1
	v_cndmask_b32_e64 v13, v13, v15, s[42:43]
	v_cndmask_b32_e32 v15, 0, v238, vcc
	v_sub_f32_e32 v13, v13, v15
	v_max_f32_e32 v13, 0xc28a0000, v13
	v_add_f32_e32 v28, v27, v13
	ds_read_u16 v13, v148 offset:1440
	s_waitcnt lgkmcnt(0)
; #define LAS __attribute__((address_space(3)))
; #define LDS_WAIT() asm volatile("s_waitcnt lgkmcnt(0)" ::: "memory")
; __device__ __forceinline__ unsigned f2bf(float f) { unsigned u = __builtin_bit_cast(unsigned, f); return (u + 0x7fffu + ((u >> 16) & 1u)) >> 16; }
; __device__ __forceinline__ float bf1(bf16 h) { return __uint_as_float(((unsigned)h) << 16); }
; __device__ __forceinline__ float sigmf(float v) { return __builtin_amdgcn_rcpf(1.0f + __builtin_amdgcn_exp2f(-1.4426950408889634f * v)); }
; __device__ __forceinline__ float siluf(float v) { return v * sigmf(v); }
; __device__ __forceinline__ bf16x8 pk8(const float* v) { v4u w = {pk2(v[0], v[1]), pk2(v[2], v[3]), pk2(v[4], v[5]), pk2(v[6], v[7])}; return __builtin_bit_cast(bf16x8, w); }
; template <bool OUT> __device__ __forceinline__ void hgrn_chunk(const PA& a, LAS unsigned char* wb, LAS float* DLk, LAS float* E7k, LAS float* DALLk, int layer, int h, int lane, const HRaw& raw, ...
;     ...
;         for (int t = 0; t < 16; ++t) { const float sg = sigmf(bf1(RF[t * 72 + lane])); const float f = lb + (1.f - lb) * sg; kk[t] = (1.f - lb) * (1.f - sg); run += fmaxf(__logf(f), -69.f); cum[t] = run; }
;         const float cl = cum[15], c7 = cum[7];
;         DLk[lane] = __expf(cl);
;         if (OUT) E7k[lane] = __expf(c7); else DALLk[lane] = cl;
;         if (OUT) {
;             float qv[16];
; #pragma unroll
;             for (int t = 0; t < 16; ++t) qv[t] = bf1(RQ[t * 72 + lane]);
;             LDS_WAIT();
; #pragma unroll
;             for (int t = 0; t < 16; ++t) {
;                 QT[t * 72 + lane] = (bf16)f2bf(siluf(qv[t]) * __expf(fminf(cum[t] - c7, 60.f)));
;                 KT[t * 72 + lane] = (bf16)f2bf(kk[t] * __expf(fminf(c7 - cum[t], 60.f)));
;             }
;         }
;         LDS_WAIT();
;         float kh[16];
; #pragma unroll
;         for (int t = 0; t < 16; ++t) kh[t] = kk[t] * __expf(cl - cum[t]);
;         *(LAS bf16x8*)(KHT + lane * 24) = pk8(kh); *(LAS bf16x8*)(KHT + lane * 24 + 8) = pk8(kh + 8);
	v_lshlrev_b32_e32 v13, 16, v13
	v_mul_f32_e32 v13, 0xbfb8aa3b, v13
	v_exp_f32_e32 v13, v13
	s_nop 0
	v_add_f32_e32 v13, 1.0, v13
	v_rcp_f32_e32 v13, v13
	s_nop 0
	v_fma_f32 v15, v2, v13, v1
	v_cmp_gt_f32_e32 vcc, s27, v15
	s_nop 1
	v_cndmask_b32_e64 v16, 0, 32, vcc
	v_ldexp_f32 v15, v15, v16
	v_log_f32_e32 v15, v15
	s_nop 0
	v_mul_f32_e32 v16, 0x3f317217, v15
	v_fma_f32 v16, v15, s80, -v16
	v_fmac_f32_e32 v16, 0x3377d1cf, v15
	v_fmac_f32_e32 v16, 0x3f317217, v15
	v_cmp_lt_f32_e64 s[42:43], |v15|, s81
	s_nop 1
	v_cndmask_b32_e64 v15, v15, v16, s[42:43]
	v_cndmask_b32_e32 v16, 0, v238, vcc
	v_sub_f32_e32 v15, v15, v16
	v_max_f32_e32 v15, 0xc28a0000, v15
	v_add_f32_e32 v29, v28, v15
	ds_read_u16 v15, v148 offset:1584
	s_waitcnt lgkmcnt(0)
	v_lshlrev_b32_e32 v15, 16, v15
	v_mul_f32_e32 v15, 0xbfb8aa3b, v15
	v_exp_f32_e32 v15, v15
	s_nop 0
	v_add_f32_e32 v15, 1.0, v15
	v_rcp_f32_e32 v15, v15
	s_nop 0
	v_fma_f32 v16, v2, v15, v1
	v_cmp_gt_f32_e32 vcc, s27, v16
	s_nop 1
	v_cndmask_b32_e64 v17, 0, 32, vcc
	v_ldexp_f32 v16, v16, v17
	v_log_f32_e32 v16, v16
	s_nop 0
	v_mul_f32_e32 v17, 0x3f317217, v16
	v_fma_f32 v17, v16, s80, -v17
	v_fmac_f32_e32 v17, 0x3377d1cf, v16
	v_fmac_f32_e32 v17, 0x3f317217, v16
	v_cmp_lt_f32_e64 s[42:43], |v16|, s81
	s_nop 1
	v_cndmask_b32_e64 v16, v16, v17, s[42:43]
	v_cndmask_b32_e32 v17, 0, v238, vcc
	v_sub_f32_e32 v16, v16, v17
	v_max_f32_e32 v16, 0xc28a0000, v16
	v_add_f32_e32 v30, v29, v16
	ds_read_u16 v16, v148 offset:1728
	s_waitcnt lgkmcnt(0)
	v_lshlrev_b32_e32 v16, 16, v16
	v_mul_f32_e32 v16, 0xbfb8aa3b, v16
	v_exp_f32_e32 v16, v16
	s_nop 0
	v_add_f32_e32 v16, 1.0, v16
	v_rcp_f32_e32 v16, v16
	s_nop 0
	v_fma_f32 v17, v2, v16, v1
	v_cmp_gt_f32_e32 vcc, s27, v17
	s_nop 1
	v_cndmask_b32_e64 v18, 0, 32, vcc
	v_ldexp_f32 v17, v17, v18
	v_log_f32_e32 v17, v17
	s_nop 0
	v_mul_f32_e32 v18, 0x3f317217, v17
	v_fma_f32 v18, v17, s80, -v18
	v_fmac_f32_e32 v18, 0x3377d1cf, v17
	v_fmac_f32_e32 v18, 0x3f317217, v17
	v_cmp_lt_f32_e64 s[42:43], |v17|, s81
	s_nop 1
	v_cndmask_b32_e64 v17, v17, v18, s[42:43]
	v_cndmask_b32_e32 v18, 0, v238, vcc
	v_sub_f32_e32 v17, v17, v18
	v_max_f32_e32 v17, 0xc28a0000, v17
	v_add_f32_e32 v31, v30, v17
	ds_read_u16 v17, v148 offset:1872
	s_waitcnt lgkmcnt(0)
	v_lshlrev_b32_e32 v17, 16, v17
	v_mul_f32_e32 v17, 0xbfb8aa3b, v17
	v_exp_f32_e32 v17, v17
	s_nop 0
	v_add_f32_e32 v17, 1.0, v17
	v_rcp_f32_e32 v18, v17
	s_nop 0
	v_fma_f32 v17, v2, v18, v1
	v_cmp_gt_f32_e32 vcc, s27, v17
	s_nop 1
	v_cndmask_b32_e64 v19, 0, 32, vcc
	v_ldexp_f32 v17, v17, v19
	v_log_f32_e32 v17, v17
	s_nop 0
	v_mul_f32_e32 v19, 0x3f317217, v17
	v_fma_f32 v19, v17, s80, -v19
	v_fmac_f32_e32 v19, 0x3377d1cf, v17
	v_fmac_f32_e32 v19, 0x3f317217, v17
	v_cmp_lt_f32_e64 s[42:43], |v17|, s81
	s_nop 1
	v_cndmask_b32_e64 v17, v17, v19, s[42:43]
	v_cndmask_b32_e32 v19, 0, v238, vcc
	v_sub_f32_e32 v17, v17, v19
	v_max_f32_e32 v17, 0xc28a0000, v17
	v_add_f32_e32 v32, v31, v17
	ds_read_u16 v17, v148 offset:2016
	s_waitcnt lgkmcnt(0)
	v_lshlrev_b32_e32 v17, 16, v17
	v_mul_f32_e32 v17, 0xbfb8aa3b, v17
	v_exp_f32_e32 v17, v17
	s_nop 0
	v_add_f32_e32 v17, 1.0, v17
	v_rcp_f32_e32 v17, v17
	s_nop 0
	v_fma_f32 v19, v2, v17, v1
	v_cmp_gt_f32_e32 vcc, s27, v19
	s_nop 1
	v_cndmask_b32_e64 v33, 0, 32, vcc
	v_ldexp_f32 v19, v19, v33
	v_log_f32_e32 v19, v19
	s_nop 0
	v_mul_f32_e32 v33, 0x3f317217, v19
	v_fma_f32 v33, v19, s80, -v33
	v_fmac_f32_e32 v33, 0x3377d1cf, v19
	v_fmac_f32_e32 v33, 0x3f317217, v19
	v_cmp_lt_f32_e64 s[42:43], |v19|, s81
	s_nop 1
	v_cndmask_b32_e64 v19, v19, v33, s[42:43]
	v_cndmask_b32_e32 v33, 0, v238, vcc
	v_sub_f32_e32 v19, v19, v33
	v_max_f32_e32 v19, 0xc28a0000, v19
	v_add_f32_e32 v33, v32, v19
	ds_read_u16 v19, v148 offset:2160
	s_waitcnt lgkmcnt(0)
	v_lshlrev_b32_e32 v19, 16, v19
	v_mul_f32_e32 v19, 0xbfb8aa3b, v19
	v_exp_f32_e32 v19, v19
	s_nop 0
	v_add_f32_e32 v19, 1.0, v19
	v_rcp_f32_e32 v19, v19
	s_nop 0
	v_fmac_f32_e32 v1, v2, v19
	v_cmp_gt_f32_e32 vcc, s27, v1
	s_nop 1
	v_cndmask_b32_e64 v34, 0, 32, vcc
	v_ldexp_f32 v1, v1, v34
	v_log_f32_e32 v1, v1
	s_nop 0
	v_mul_f32_e32 v34, 0x3f317217, v1
	v_fma_f32 v34, v1, s80, -v34
	v_fmac_f32_e32 v34, 0x3377d1cf, v1
	v_fmac_f32_e32 v34, 0x3f317217, v1
	v_cmp_lt_f32_e64 s[42:43], |v1|, s81
	s_nop 1
	v_cndmask_b32_e64 v1, v1, v34, s[42:43]
	v_cndmask_b32_e32 v34, 0, v238, vcc
	v_sub_f32_e32 v1, v1, v34
	v_max_f32_e32 v1, 0xc28a0000, v1
	v_add_f32_e32 v1, v33, v1
	v_mul_f32_e32 v34, 0x3fb8aa3b, v1
	v_exp_f32_e32 v34, v34
	v_sub_f32_e32 v3, v1, v3
	v_mul_f32_e32 v3, 0x3fb8aa3b, v3
	ds_write_b32 v149, v34 offset:11520
	ds_write_b32 v150, v1
	v_exp_f32_e32 v34, v3
	v_sub_f32_e32 v3, v1, v20
	v_mul_f32_e32 v3, 0x3fb8aa3b, v3
	v_exp_f32_e32 v20, v3
	v_sub_f32_e32 v3, v1, v21
	v_mul_f32_e32 v3, 0x3fb8aa3b, v3
	v_exp_f32_e32 v35, v3
	v_sub_f32_e32 v3, v1, v22
	v_mul_f32_e32 v3, 0x3fb8aa3b, v3
	v_exp_f32_e32 v21, v3
	v_sub_f32_e32 v3, v1, v23
	v_mul_f32_e32 v3, 0x3fb8aa3b, v3
	v_exp_f32_e32 v22, v3
	v_sub_f32_e32 v3, v1, v24
	v_mul_f32_e32 v3, 0x3fb8aa3b, v3
	v_exp_f32_e32 v24, v3
	v_sub_f32_e32 v3, v1, v25
	v_mul_f32_e32 v3, 0x3fb8aa3b, v3
	v_exp_f32_e32 v23, v3
	v_sub_f32_e32 v3, v1, v26
	v_mul_f32_e32 v3, 0x3fb8aa3b, v3
	v_exp_f32_e32 v25, v3
	v_sub_f32_e32 v3, v1, v27
	v_mul_f32_e32 v3, 0x3fb8aa3b, v3
	v_exp_f32_e32 v26, v3
	v_sub_f32_e32 v3, v1, v28
	v_mul_f32_e32 v3, 0x3fb8aa3b, v3
	v_exp_f32_e32 v28, v3
	v_sub_f32_e32 v3, v1, v29
	v_mul_f32_e32 v3, 0x3fb8aa3b, v3
	v_exp_f32_e32 v27, v3
	v_sub_f32_e32 v3, v1, v30
	v_mul_f32_e32 v3, 0x3fb8aa3b, v3
	v_exp_f32_e32 v29, v3
	v_sub_f32_e32 v3, v1, v31
	v_mul_f32_e32 v3, 0x3fb8aa3b, v3
	v_exp_f32_e32 v30, v3
	v_sub_f32_e32 v3, v1, v32
	v_mul_f32_e32 v3, 0x3fb8aa3b, v3
	v_exp_f32_e32 v32, v3
	v_sub_f32_e32 v3, v1, v33
	v_mul_f32_e32 v3, 0x3fb8aa3b, v3
	v_sub_f32_e32 v1, v1, v1
	v_pk_mul_f32 v[6:7], v[2:3], v[6:7] op_sel_hi:[0,1]
	v_pk_mul_f32 v[10:11], v[2:3], v[10:11] op_sel_hi:[0,1]
	v_mul_f32_e32 v1, 0x3fb8aa3b, v1
	v_pk_mul_f32 v[4:5], v[2:3], v[4:5] op_sel_hi:[0,1]
	v_pk_mul_f32 v[6:7], v[6:7], v[20:21]
	v_pk_mul_f32 v[8:9], v[2:3], v[8:9] op_sel_hi:[0,1]
	v_pk_mul_f32 v[10:11], v[10:11], v[24:25]
	v_exp_f32_e32 v31, v3
	v_exp_f32_e32 v33, v1
	v_pk_mul_f32 v[4:5], v[4:5], v[34:35]
	v_pk_mul_f32 v[8:9], v[8:9], v[22:23]
	v_bfe_u32 v1, v11, 16, 1
	v_bfe_u32 v3, v10, 16, 1
	v_bfe_u32 v20, v7, 16, 1
	v_bfe_u32 v21, v6, 16, 1
	v_add3_u32 v21, v6, v21, s73
	v_add3_u32 v20, v7, v20, s73
	v_add3_u32 v3, v10, v3, s73
	v_add3_u32 v1, v11, v1, s73
	v_bfe_u32 v6, v8, 16, 1
	v_bfe_u32 v7, v9, 16, 1
	v_bfe_u32 v10, v4, 16, 1
	v_bfe_u32 v11, v5, 16, 1
	v_add3_u32 v7, v9, v7, s73
	v_add3_u32 v6, v8, v6, s73
	v_add3_u32 v5, v5, v11, s73
	v_add3_u32 v4, v4, v10, s73
	v_lshrrev_b32_e32 v6, 16, v6
	v_lshrrev_b32_e32 v7, 16, v7
	v_lshrrev_b32_e32 v4, 16, v4
	v_lshrrev_b32_e32 v5, 16, v5
	v_and_or_b32 v7, v1, s26, v7
	v_and_or_b32 v6, v3, s26, v6
	v_and_or_b32 v5, v20, s26, v5
	v_and_or_b32 v4, v21, s26, v4
	s_waitcnt lgkmcnt(0)
; #define LAS __attribute__((address_space(3)))
; #define LDS_WAIT() asm volatile("s_waitcnt lgkmcnt(0)" ::: "memory")
; __device__ __forceinline__ bf16x8 pk8(const float* v) { v4u w = {pk2(v[0], v[1]), pk2(v[2], v[3]), pk2(v[4], v[5]), pk2(v[6], v[7])}; return __builtin_bit_cast(bf16x8, w); }
; #define HG_LAUNDER() do { asm volatile("" : "+v"(lane)); l15 = lane & 15; q = lane >> 4; } while (0)
; template <bool OUT> __device__ __forceinline__ void hgrn_chunk(const PA& a, LAS unsigned char* wb, LAS float* DLk, LAS float* E7k, LAS float* DALLk, int layer, int h, int lane, const HRaw& raw, ...
;     ...
;         *(LAS bf16x8*)(KHT + lane * 24) = pk8(kh); *(LAS bf16x8*)(KHT + lane * 24 + 8) = pk8(kh + 8);
;     }
;     LDS_WAIT();
;     bf16x8 vfr[4];
; #pragma unroll
;     for (int nt = 0; nt < 4; ++nt) vfr[nt] = (q < 2) ? *(const LAS bf16x8*)(VT + (16 * nt + l15) * 24 + q * 8) : zero8;
; #pragma unroll
;     for (int mt = 0; mt < 4; ++mt) { const bf16x8 afr = (q < 2) ? *(const LAS bf16x8*)(KHT + (16 * mt + l15) * 24 + q * 8) : zero8;
; #pragma unroll
;         for (int nt = 0; nt < 4; ++nt) U[mt][nt] = __builtin_amdgcn_mfma_f32_16x16x32_bf16(afr, vfr[nt], (f32x4){0.f, 0.f, 0.f, 0.f}, 0, 0, 0); }
; template <bool OUT> __device__ __forceinline__ void hgrn_pair(const PA& a, LAS unsigned char* lds, int layer, int bh, int s, int wave, int lane) {
;     ...
;     { const HRaw r0 = hgrn_loadc<OUT>(a, bh, c, 2 * wl, lane); hgrn_chunk<OUT>(a, wb, DLs, DLs + 128, DALL + (2 * wl) * 64, layer, h, lane, r0, U0, o[0], qf[0]); }
;     asm volatile("" ::: "memory"); __builtin_amdgcn_sched_barrier(0); HG_LAUNDER();
;     { const HRaw r1 = hgrn_loadc<OUT>(a, bh, c, 2 * wl + 1, lane); hgrn_chunk<OUT>(a, wb, DLs + 64, DLs + 192, DALL + (2 * wl + 1) * 64, layer, h, lane, r1, Up, o[1], qf[1]); }
	ds_write_b128 v151, v[4:7] offset:4608
	v_pk_add_f32 v[4:5], v[12:13], 1.0 op_sel_hi:[1,0] neg_lo:[1,0] neg_hi:[1,0]
	v_pk_add_f32 v[6:7], v[14:15], 1.0 op_sel_hi:[1,0] neg_lo:[1,0] neg_hi:[1,0]
	v_pk_add_f32 v[8:9], v[16:17], 1.0 op_sel_hi:[1,0] neg_lo:[1,0] neg_hi:[1,0]
	v_pk_add_f32 v[10:11], v[18:19], 1.0 op_sel_hi:[1,0] neg_lo:[1,0] neg_hi:[1,0]
	v_pk_mul_f32 v[4:5], v[2:3], v[4:5] op_sel_hi:[0,1]
	v_pk_mul_f32 v[6:7], v[2:3], v[6:7] op_sel_hi:[0,1]
	v_pk_mul_f32 v[8:9], v[2:3], v[8:9] op_sel_hi:[0,1]
	v_pk_mul_f32 v[2:3], v[2:3], v[10:11] op_sel_hi:[0,1]
	v_pk_mul_f32 v[6:7], v[6:7], v[28:29]
	v_pk_mul_f32 v[2:3], v[2:3], v[32:33]
	v_pk_mul_f32 v[4:5], v[4:5], v[26:27]
	v_pk_mul_f32 v[8:9], v[8:9], v[30:31]
	v_bfe_u32 v1, v7, 16, 1
	v_bfe_u32 v10, v6, 16, 1
	v_bfe_u32 v11, v3, 16, 1
	v_bfe_u32 v12, v2, 16, 1
	v_add3_u32 v6, v6, v10, s73
	v_add3_u32 v1, v7, v1, s73
	v_add3_u32 v7, v2, v12, s73
	v_add3_u32 v10, v3, v11, s73
	v_bfe_u32 v2, v8, 16, 1
	v_bfe_u32 v3, v9, 16, 1
	v_bfe_u32 v11, v4, 16, 1
	v_bfe_u32 v12, v5, 16, 1
	v_add3_u32 v5, v5, v12, s73
	v_add3_u32 v4, v4, v11, s73
	v_add3_u32 v3, v9, v3, s73
	v_add3_u32 v2, v8, v2, s73
	v_lshrrev_b32_e32 v8, 16, v2
	v_lshrrev_b32_e32 v9, 16, v3
	v_lshrrev_b32_e32 v2, 16, v4
	v_lshrrev_b32_e32 v3, 16, v5
	v_and_or_b32 v3, v1, s26, v3
	v_and_or_b32 v2, v6, s26, v2
	v_and_or_b32 v5, v10, s26, v9
	v_and_or_b32 v4, v7, s26, v8
	ds_write_b128 v151, v[2:5] offset:4624
	s_waitcnt lgkmcnt(0)
	v_mov_b32_e32 v1, 0
	v_mov_b32_e32 v2, 0
	v_mov_b32_e32 v3, 0
	s_and_saveexec_b64 s[2:3], s[40:41]
	ds_read_b128 v[0:3], v152 offset:7680
	s_or_b64 exec, exec, s[2:3]
	v_mov_b32_e32 v4, 0
	v_mov_b32_e32 v8, 0
	v_mov_b32_e32 v9, 0
	v_mov_b32_e32 v10, 0
	v_mov_b32_e32 v11, 0
	s_and_saveexec_b64 s[2:3], s[40:41]
	ds_read_b128 v[8:11], v152 offset:8448
	s_or_b64 exec, exec, s[2:3]
	v_mov_b32_e32 v5, 0
	v_mov_b32_e32 v6, 0
	v_mov_b32_e32 v7, 0
	s_and_saveexec_b64 s[2:3], s[40:41]
	ds_read_b128 v[4:7], v152 offset:9216
	s_or_b64 exec, exec, s[2:3]
	v_mov_b32_e32 v12, 0
	v_mov_b32_e32 v64, 0
	v_mov_b32_e32 v65, 0
	v_mov_b32_e32 v66, 0
	v_mov_b32_e32 v67, 0
	s_and_saveexec_b64 s[2:3], s[40:41]
	ds_read_b128 v[64:67], v152 offset:9984
	s_or_b64 exec, exec, s[2:3]
	v_mov_b32_e32 v13, 0
	v_mov_b32_e32 v14, 0
	v_mov_b32_e32 v15, 0
	s_and_saveexec_b64 s[2:3], s[40:41]
	ds_read_b128 v[12:15], v152 offset:4608
	s_or_b64 exec, exec, s[2:3]
	s_waitcnt lgkmcnt(0)
	v_mfma_f32_16x16x32_bf16 v[60:63], v[12:15], v[0:3], 0
	v_mov_b32_e32 v16, 0
	v_mov_b32_e32 v17, 0
	v_mfma_f32_16x16x32_bf16 v[56:59], v[12:15], v[8:11], 0
	v_mfma_f32_16x16x32_bf16 v[52:55], v[12:15], v[4:7], 0
	v_mfma_f32_16x16x32_bf16 v[48:51], v[12:15], v[64:67], 0
	v_mov_b32_e32 v12, 0
	v_mov_b32_e32 v14, 0
	v_mov_b32_e32 v15, 0
	s_and_saveexec_b64 s[2:3], s[40:41]
	ds_read_b128 v[14:17], v152 offset:5376
	s_or_b64 exec, exec, s[2:3]
	s_waitcnt lgkmcnt(0)
	v_mfma_f32_16x16x32_bf16 v[44:47], v[14:17], v[0:3], 0
	v_mov_b32_e32 v13, 0
	v_mfma_f32_16x16x32_bf16 v[40:43], v[14:17], v[8:11], 0
	v_mfma_f32_16x16x32_bf16 v[36:39], v[14:17], v[4:7], 0
	v_mfma_f32_16x16x32_bf16 v[32:35], v[14:17], v[64:67], 0
	v_mov_b32_e32 v14, 0
	v_mov_b32_e32 v15, 0
	s_and_saveexec_b64 s[2:3], s[40:41]
	ds_read_b128 v[12:15], v152 offset:6144
	s_or_b64 exec, exec, s[2:3]
	s_waitcnt lgkmcnt(0)
	v_mfma_f32_16x16x32_bf16 v[28:31], v[12:15], v[0:3], 0
	v_mov_b32_e32 v80, 0
	v_mov_b32_e32 v68, 0
	v_mov_b32_e32 v69, 0
	v_mfma_f32_16x16x32_bf16 v[24:27], v[12:15], v[8:11], 0
	v_mov_b32_e32 v70, 0
	v_mov_b32_e32 v71, 0
	v_mfma_f32_16x16x32_bf16 v[20:23], v[12:15], v[4:7], 0
	v_mfma_f32_16x16x32_bf16 v[16:19], v[12:15], v[64:67], 0
	s_and_saveexec_b64 s[2:3], s[40:41]
	ds_read_b128 v[68:71], v152 offset:6912
	s_or_b64 exec, exec, s[2:3]
	s_waitcnt lgkmcnt(0)
	v_mfma_f32_16x16x32_bf16 v[12:15], v[68:71], v[0:3], 0
	v_mfma_f32_16x16x32_bf16 v[8:11], v[68:71], v[8:11], 0
	v_mfma_f32_16x16x32_bf16 v[4:7], v[68:71], v[4:7], 0
	v_mfma_f32_16x16x32_bf16 v[0:3], v[68:71], v[64:67], 0
	v_mov_b32_e32 v144, v140
	s_or_b64 s[2:3], s[24:25], s[12:13]
	v_ashrrev_i32_e32 v82, 3, v144
	v_ashrrev_i32_e32 v83, 31, v82
	v_lshl_add_u64 v[64:65], s[2:3], 0, v[82:83]
	v_mov_b64_e32 v[66:67], s[60:61]
	v_mad_u64_u32 v[66:67], s[2:3], v64, s93, v[66:67]
	v_mov_b32_e32 v64, v67
	v_mad_u64_u32 v[64:65], s[2:3], v65, s93, v[64:65]
	v_mov_b32_e32 v67, v64
	v_lshl_add_u64 v[64:65], v[66:67], 0, s[62:63]
	v_lshlrev_b32_e32 v66, 4, v144
	v_and_b32_e32 v84, 0x70, v66
	v_mov_b32_e32 v85, v221
	v_lshl_add_u64 v[72:73], v[64:65], 0, v[84:85]
	v_add_co_u32_e32 v76, vcc, s55, v72
	v_addc_co_u32_e32 v77, vcc, 0, v73, vcc
	s_movk_i32 s2, 0x90
	v_mul_lo_u32 v81, v82, s2
	v_add3_u32 v81, s9, v84, v81
	s_waitcnt lgkmcnt(0)
	s_and_b64 vcc, exec, s[0:1]
	s_waitcnt vmcnt(0)
	ds_write_b128 v81, v[160:163]
	ds_write_b128 v81, v[164:167] offset:2304
	ds_write_b128 v81, v[168:171] offset:1152
	ds_write_b128 v81, v[172:175] offset:3456
	s_waitcnt lgkmcnt(0)
	s_cbranch_vccnz .LBB0_480
	v_mov_b32_e32 v80, v177
